# layer 0 in-proj weight conversion done in phase 0 by the 256 workgroups without a phase-0 item
# baseline (speedup 1.0000x reference)
_Z2mk6Paramsii:
	s_load_dwordx2 s[30:31], s[0:1], 0x138
	s_load_dword s42, s[0:1], 0x140
	s_mov_b64 s[74:75], s[0:1]
	s_add_u32 s80, s74, 0x140
	s_addc_u32 s81, s75, 0
	s_waitcnt lgkmcnt(0)
	s_sub_i32 s0, s31, s30
	s_mov_b32 s66, s2
	s_mov_b32 s101, 0
	s_mov_b32 s100, 0
	s_cmp_lt_i32 s0, 2
	s_cbranch_scc1 .LBB0_5
	v_and_b32_e32 v1, 0x3ff, v0
	s_nop 0
	v_cmp_eq_u32_e32 vcc, 0, v1
	s_and_saveexec_b64 s[0:1], vcc
	s_cbranch_execz .LBB0_4
	s_add_i32 s2, 0, 0x10010
	v_mov_b32_e32 v2, 0
	s_mov_b64 s[4:5], exec
	v_mov_b32_e32 v3, v2
	v_mov_b32_e32 v4, v2
	v_mov_b32_e32 v5, v2
	v_mov_b32_e32 v1, s2
	ds_write_b128 v1, v[2:5]
	v_mbcnt_lo_u32_b32 v1, s4, 0
	v_mbcnt_hi_u32_b32 v1, s5, v1
	v_cmp_eq_u32_e32 vcc, 0, v1
	s_getreg_b32 s2, hwreg(HW_REG_XCC_ID, 0, 4)
	s_and_b64 s[6:7], exec, vcc
	s_mov_b64 exec, s[6:7]
	s_cbranch_execz .LBB0_4
	s_load_dwordx2 s[6:7], s[74:75], 0x130
	s_lshl_b32 s2, s2, 8
	s_and_b32 s2, s2, 0xf00
	v_mov_b32_e32 v1, 0x24000
	s_waitcnt lgkmcnt(0)
	s_add_u32 s2, s6, s2
	s_addc_u32 s3, s7, 0
	s_bcnt1_i32_b64 s4, s[4:5]
	v_mov_b32_e32 v2, s4
	global_atomic_add v1, v2, s[2:3] offset:1280

.LBB0_853:
	s_cmp_eq_u32 s62, 0
	s_cbranch_scc1 .LBB0_942
	s_load_dwordx2 s[6:7], s[0:1], 0x130
	s_waitcnt lgkmcnt(0)
	v_mov_b32_e32 v2, v133
	v_lshrrev_b32_e32 v3, 4, v2
	v_and_b32_e32 v4, 15, v2
	v_lshlrev_b32_e32 v4, 2, v4
	v_mul_u32_u24_e32 v5, 65, v3
	v_add_lshl_u32 v5, v5, v4, 2
	v_and_b32_e32 v7, 63, v2
	v_lshrrev_b32_e32 v27, 6, v2
	v_and_b32_e32 v24, 15, v7
	v_lshrrev_b32_e32 v25, 4, v7
	v_readfirstlane_b32 s22, v27
	v_mul_u32_u24_e32 v6, 520, v25
	v_lshl_add_u32 v6, v27, 4, v6
	v_add_lshl_u32 v6, v6, v24, 2
	v_lshlrev_b32_e32 v26, 4, v7
	s_sub_u32 s14, s24, 2048
	s_mov_b32 s25, s14
	s_cmp_ge_u32 s25, 656
	s_cbranch_scc1 .Lcp_dec_zero_f
	s_cmp_lt_u32 s25, 656
	s_cbranch_scc1 .Lcp_dec_win_f
	s_cmp_lt_u32 s25, 1680
	s_cbranch_scc1 .Lcp_dec_wm_f
	s_cmp_lt_u32 s25, 1936
	s_cbranch_scc1 .Lcp_dec_wb_f
	s_cmp_lt_u32 s25, 2192
	s_cbranch_scc1 .Lcp_dec_wout_f
	s_cmp_lt_u32 s25, 3216
	s_cbranch_scc1 .Lcp_dec_w1_f
	s_cmp_lt_u32 s25, 4240
	s_cbranch_scc1 .Lcp_dec_w2_f
	s_branch .Lcp_dec_zero_f

.Lph0_conv:
	s_waitcnt lgkmcnt(0)
	v_mov_b32_e32 v2, v133
	v_lshrrev_b32_e32 v3, 4, v2
	v_and_b32_e32 v4, 15, v2
	v_lshlrev_b32_e32 v4, 2, v4
	v_mul_u32_u24_e32 v5, 65, v3
	v_add_lshl_u32 v5, v5, v4, 2
	v_and_b32_e32 v7, 63, v2
	v_lshrrev_b32_e32 v27, 6, v2
	v_and_b32_e32 v24, 15, v7
	v_lshrrev_b32_e32 v25, 4, v7
	v_readfirstlane_b32 s22, v27
	v_mul_u32_u24_e32 v6, 520, v25
	v_lshl_add_u32 v6, v27, 4, v6
	v_add_lshl_u32 v6, v6, v24, 2
	v_lshlrev_b32_e32 v26, 4, v7
	s_sub_u32 s14, s24, 2048
	s_mov_b32 s25, s14
	s_cmp_ge_u32 s25, 656
	s_cbranch_scc1 .Lcr_dec_zero_f
	s_cmp_lt_u32 s25, 656
	s_cbranch_scc1 .Lcr_dec_win_f
	s_cmp_lt_u32 s25, 1680
	s_cbranch_scc1 .Lcr_dec_wm_f
	s_cmp_lt_u32 s25, 1936
	s_cbranch_scc1 .Lcr_dec_wb_f
	s_cmp_lt_u32 s25, 2192
	s_cbranch_scc1 .Lcr_dec_wout_f
	s_cmp_lt_u32 s25, 3216
	s_cbranch_scc1 .Lcr_dec_w1_f
	s_cmp_lt_u32 s25, 4240
	s_cbranch_scc1 .Lcr_dec_w2_f
	s_branch .Lcr_dec_zero_f

.Lcr_dec_done_f:
.Lcr_loop:
	s_add_u32 s15, s24, 256
	s_mov_b32 s12, 5
	s_mov_b32 s16, 0
	s_cmp_gt_u32 s15, 0xa90
	s_cbranch_scc1 .Lcr_noA
	s_sub_u32 s14, s15, 2048
	s_mov_b32 s25, s14
	s_cmp_ge_u32 s25, 656
	s_cbranch_scc1 .Lcr_dec_zero_a
	s_cmp_lt_u32 s25, 656
	s_cbranch_scc1 .Lcr_dec_win_a
	s_cmp_lt_u32 s25, 1680
	s_cbranch_scc1 .Lcr_dec_wm_a
	s_cmp_lt_u32 s25, 1936
	s_cbranch_scc1 .Lcr_dec_wb_a
	s_cmp_lt_u32 s25, 2192
	s_cbranch_scc1 .Lcr_dec_wout_a
	s_cmp_lt_u32 s25, 3216
	s_cbranch_scc1 .Lcr_dec_w1_a
	s_cmp_lt_u32 s25, 4240
	s_cbranch_scc1 .Lcr_dec_w2_a
	s_branch .Lcr_dec_zero_a

.Lcr_pdone_a:
	s_cmp_eq_u32 s12, 5
	s_cbranch_scc1 .Lcr_exit
	s_mov_b32 s24, s15
	s_add_u32 s15, s24, 256
	s_mov_b32 s9, 5
	s_mov_b32 s16, 0
	s_cmp_gt_u32 s15, 0xa90
	s_cbranch_scc1 .Lcr_noB
	s_sub_u32 s14, s15, 2048
	s_mov_b32 s25, s14
	s_cmp_ge_u32 s25, 656
	s_cbranch_scc1 .Lcr_dec_zero_b
	s_cmp_lt_u32 s25, 656
	s_cbranch_scc1 .Lcr_dec_win_b
	s_cmp_lt_u32 s25, 1680
	s_cbranch_scc1 .Lcr_dec_wm_b
	s_cmp_lt_u32 s25, 1936
	s_cbranch_scc1 .Lcr_dec_wb_b
	s_cmp_lt_u32 s25, 2192
	s_cbranch_scc1 .Lcr_dec_wout_b
	s_cmp_lt_u32 s25, 3216
	s_cbranch_scc1 .Lcr_dec_w1_b
	s_cmp_lt_u32 s25, 4240
	s_cbranch_scc1 .Lcr_dec_w2_b
	s_branch .Lcr_dec_zero_b

.LBB0_963:
	s_cmp_lg_u32 s30, 0
	s_cbranch_scc1 .Lc0_skip
	s_cmp_eq_u32 s100, 2
	s_cbranch_scc1 .Lc0_done
	s_cmp_lt_u32 s66, 256
	s_cbranch_scc1 .Lc0_skip
	s_mov_b32 s100, 2
	s_mov_b32 s62, 0
	s_add_i32 s24, s66, 0x700
	s_load_dwordx2 s[6:7], s[0:1], 0x130
	s_branch .Lph0_conv
.Lc0_done:
	s_mov_b32 s100, 0
